# P1 row loop: cross-row sumsq/amax reductions via v_permlane16/32_swap instead of ds_bpermute round trips
# speedup vs baseline: 1.0061x; 1.0061x over previous
.LBB0_210:
	v_add_u32_e32 v65, s30, v32
	s_movk_i32 s8, 0x7fff
	v_cmp_gt_i32_e32 vcc, s19, v65
	v_cmp_lt_i32_e64 s[8:9], s8, v65
	v_ashrrev_i32_e32 v24, 11, v32
	v_mul_i32_i24_e32 v24, 0x1800, v24
	s_mov_b64 s[10:11], 0x1000
	v_ashrrev_i32_e32 v25, 31, v24
	v_lshl_add_u64 v[24:25], v[24:25], 2, s[86:87]
	v_lshl_add_u64 v[32:33], v[24:25], 0, s[10:11]
	v_lshl_add_u64 v[60:61], v[24:25], 0, v[40:41]
	v_lshl_add_u64 v[26:27], v[32:33], 0, v[40:41]
	v_lshl_add_u64 v[28:29], v[32:33], 0, v[50:51]
	v_lshl_add_u64 v[30:31], v[32:33], 0, v[52:53]
	v_lshl_add_u64 v[32:33], v[32:33], 0, v[54:55]
	global_load_dwordx4 v[76:79], v[42:43], off
	global_load_dwordx4 v[80:83], v[42:43], off offset:1024
	global_load_dwordx4 v[84:87], v[42:43], off offset:2048
	global_load_dwordx4 v[88:91], v[42:43], off offset:3072
	global_load_dwordx4 v[92:95], v[26:27], off
	global_load_dwordx4 v[96:99], v[28:29], off
	global_load_dwordx4 v[100:103], v[30:31], off
	global_load_dwordx4 v[104:107], v[32:33], off
	global_load_dwordx4 v[108:111], v[60:61], off
	global_load_dwordx4 v[112:115], v[60:61], off offset:1024
	global_load_dwordx4 v[116:119], v[60:61], off offset:2048
	global_load_dwordx4 v[120:123], v[60:61], off offset:3072
	s_sub_u32 s24, 0, s12
	s_subb_u32 s25, 0, s13
	v_lshl_add_u64 v[124:125], v[48:49], 0, s[24:25]
	v_cndmask_b32_e32 v126, v124, v48, vcc
	v_cndmask_b32_e32 v127, v125, v49, vcc
	global_load_dwordx4 v[4:7], v[126:127], off
	global_load_dwordx4 v[8:11], v[126:127], off offset:1024
	global_load_dwordx4 v[12:15], v[126:127], off offset:2048
	global_load_dwordx4 v[16:19], v[126:127], off offset:3072
	v_pk_mul_f32 v[24:25], v[20:21], v[20:21]
	v_pk_mul_f32 v[26:27], v[0:1], v[0:1]
	v_pk_fma_f32 v[24:25], v[36:37], v[36:37], v[24:25]
	v_pk_fma_f32 v[26:27], v[58:59], v[58:59], v[26:27]
	v_pk_fma_f32 v[24:25], v[22:23], v[22:23], v[24:25]
	v_pk_fma_f32 v[26:27], v[2:3], v[2:3], v[26:27]
	v_pk_fma_f32 v[24:25], v[34:35], v[34:35], v[24:25]
	v_pk_fma_f32 v[26:27], v[56:57], v[56:57], v[26:27]
	v_add_f32_e32 v24, v24, v25
	v_add_f32_e32 v24, v27, v24
	v_add_f32_e32 v24, v26, v24
	s_mov_b32 s10, 0x800000
	v_add_f32_dpp v24, v24, v24 row_ror:8 row_mask:0xf bank_mask:0xf bound_ctrl:1
	s_nop 1
	v_add_f32_dpp v24, v24, v24 row_ror:4 row_mask:0xf bank_mask:0xf bound_ctrl:1
	s_nop 1
	v_add_f32_dpp v24, v24, v24 row_ror:2 row_mask:0xf bank_mask:0xf bound_ctrl:1
	s_nop 1
	v_add_f32_dpp v24, v24, v24 row_ror:1 row_mask:0xf bank_mask:0xf bound_ctrl:1
	s_nop 1
	v_mov_b32_e32 v25, v24
	s_nop 1
	v_permlane16_swap_b32_e32 v25, v24
	s_nop 1
	v_add_f32_e32 v24, v24, v25
	s_nop 1
	v_mov_b32_e32 v25, v24
	s_nop 1
	v_permlane32_swap_b32_e32 v25, v24
	s_nop 1
	v_add_f32_e32 v24, v24, v25
	v_fmamk_f32 v24, v24, 0x3a800000, v64
	v_cmp_gt_f32_e32 vcc, s10, v24
	v_mul_f32_e32 v25, 0x4b800000, v24
	v_cndmask_b32_e32 v24, v24, v25, vcc
	v_rsq_f32_e32 v24, v24
	s_nop 0
	v_mul_f32_e32 v25, 0x45800000, v24
	v_cndmask_b32_e32 v66, v24, v25, vcc
	s_waitcnt vmcnt(4)
	v_mul_f32_e32 v142, v21, v66
	v_add_f32_e32 v143, 1.0, v92
	v_mul_f32_e32 v142, v76, v142
	v_fma_f32 v24, v143, v142, v108
	v_mul_f32_e32 v142, v37, v66
	v_add_f32_e32 v143, 1.0, v93
	v_mul_f32_e32 v142, v77, v142
	v_fma_f32 v25, v143, v142, v109
	v_mul_f32_e32 v142, v23, v66
	v_add_f32_e32 v143, 1.0, v94
	v_mul_f32_e32 v142, v78, v142
	v_fma_f32 v26, v143, v142, v110
	v_mul_f32_e32 v142, v35, v66
	v_add_f32_e32 v143, 1.0, v95
	v_mul_f32_e32 v142, v79, v142
	v_fma_f32 v27, v143, v142, v111
	v_mul_f32_e32 v142, v20, v66
	v_add_f32_e32 v143, 1.0, v96
	v_mul_f32_e32 v142, v80, v142
	v_fma_f32 v28, v143, v142, v112
	v_mul_f32_e32 v142, v36, v66
	v_add_f32_e32 v143, 1.0, v97
	v_mul_f32_e32 v142, v81, v142
	v_fma_f32 v67, v143, v142, v113
	v_mul_f32_e32 v142, v22, v66
	v_add_f32_e32 v143, 1.0, v98
	v_mul_f32_e32 v142, v82, v142
	v_fma_f32 v29, v143, v142, v114
	v_mul_f32_e32 v142, v34, v66
	v_add_f32_e32 v143, 1.0, v99
	v_mul_f32_e32 v142, v83, v142
	v_fma_f32 v31, v143, v142, v115
	v_mul_f32_e32 v142, v1, v66
	v_add_f32_e32 v143, 1.0, v100
	v_mul_f32_e32 v142, v84, v142
	v_fma_f32 v1, v143, v142, v116
	v_mul_f32_e32 v142, v59, v66
	v_add_f32_e32 v143, 1.0, v101
	v_mul_f32_e32 v142, v85, v142
	v_fma_f32 v59, v143, v142, v117
	v_mul_f32_e32 v142, v3, v66
	v_add_f32_e32 v143, 1.0, v102
	v_mul_f32_e32 v142, v86, v142
	v_fma_f32 v3, v143, v142, v118
	v_mul_f32_e32 v142, v57, v66
	v_add_f32_e32 v143, 1.0, v103
	v_mul_f32_e32 v142, v87, v142
	v_fma_f32 v23, v143, v142, v119
	v_mul_f32_e32 v142, v0, v66
	v_add_f32_e32 v143, 1.0, v104
	v_mul_f32_e32 v142, v88, v142
	v_fma_f32 v20, v143, v142, v120
	v_mul_f32_e32 v142, v58, v66
	v_add_f32_e32 v143, 1.0, v105
	v_mul_f32_e32 v142, v89, v142
	v_fma_f32 v21, v143, v142, v121
	v_mul_f32_e32 v142, v2, v66
	v_add_f32_e32 v143, 1.0, v106
	v_mul_f32_e32 v142, v90, v142
	v_fma_f32 v2, v143, v142, v122
	v_mul_f32_e32 v142, v56, v66
	v_add_f32_e32 v143, 1.0, v107
	v_mul_f32_e32 v142, v91, v142
	v_fma_f32 v35, v143, v142, v123
	v_max_f32_e64 v30, |v26|, |v27|
	v_max3_f32 v30, |v24|, |v25|, v30
	v_max3_f32 v30, |v28|, |v67|, v30
	v_max3_f32 v30, |v29|, |v31|, v30
	v_max3_f32 v30, |v1|, |v59|, v30
	v_max3_f32 v30, |v3|, |v23|, v30
	v_max3_f32 v30, |v20|, |v21|, v30
	v_max3_f32 v0, |v2|, |v35|, v30
	s_nop 1
	v_mov_b32_dpp v22, v0 row_ror:8 row_mask:0xf bank_mask:0xf bound_ctrl:1
	v_max_f32_e32 v22, v22, v22
	v_max_f32_e32 v0, v0, v22
	s_nop 1
	v_mov_b32_dpp v22, v0 row_ror:4 row_mask:0xf bank_mask:0xf bound_ctrl:1
	v_max_f32_e32 v22, v22, v22
	v_max_f32_e32 v0, v0, v22
	s_nop 1
	v_mov_b32_dpp v22, v0 row_ror:2 row_mask:0xf bank_mask:0xf bound_ctrl:1
	v_max_f32_e32 v22, v22, v22
	v_max_f32_e32 v0, v0, v22
	s_nop 1
	v_mov_b32_dpp v22, v0 row_ror:1 row_mask:0xf bank_mask:0xf bound_ctrl:1
	v_max_f32_e32 v22, v22, v22
	v_max_f32_e32 v0, v0, v22
	s_nop 1
	v_mov_b32_e32 v22, v0
	s_nop 1
	v_permlane16_swap_b32_e32 v22, v0
	s_nop 1
	v_max_f32_e32 v0, v0, v22
	s_nop 1
	v_mov_b32_e32 v22, v0
	s_nop 1
	v_permlane32_swap_b32_e32 v22, v0
	s_nop 1
	v_max_f32_e32 v0, v0, v22
	v_div_scale_f32 v22, s[16:17], v0, v0, s20
	v_rcp_f32_e32 v30, v22
	v_cmp_lt_f32_e64 s[10:11], 0, v0
	v_fma_f32 v32, -v22, v30, 1.0
	v_fmac_f32_e32 v30, v32, v30
	v_div_scale_f32 v32, vcc, s20, v0, s20
	v_mul_f32_e32 v33, v32, v30
	v_fma_f32 v34, -v22, v33, v32
	v_fmac_f32_e32 v33, v34, v30
	v_fma_f32 v22, -v22, v33, v32
	v_div_fmas_f32 v22, v22, v30, v33
	v_div_fixup_f32 v22, v22, v0, s20
	v_cndmask_b32_e64 v22, 1.0, v22, s[10:11]
	v_mul_f32_e32 v24, v24, v22
	v_mul_f32_e32 v25, v25, v22
	v_mov_b32_e32 v30, 0
	v_cvt_pk_fp8_f32 v30, v24, v25
	v_mul_f32_e32 v24, v26, v22
	v_mul_f32_e32 v25, v27, v22
	v_mov_b32_e32 v26, 0
	v_cvt_pk_fp8_f32 v30, v24, v25 op_sel:[0,0,1]
	v_mul_f32_e32 v24, v28, v22
	v_mul_f32_e32 v25, v67, v22
	v_cvt_pk_fp8_f32 v26, v24, v25
	v_mul_f32_e32 v24, v29, v22
	v_mul_f32_e32 v25, v31, v22
	v_mul_f32_e32 v1, v1, v22
	v_cvt_pk_fp8_f32 v26, v24, v25 op_sel:[0,0,1]
	v_mul_f32_e32 v24, v59, v22
	v_mov_b32_e32 v25, 0
	v_cvt_pk_fp8_f32 v25, v1, v24
	v_mul_f32_e32 v1, v3, v22
	v_mul_f32_e32 v3, v23, v22
	global_store_dword v[46:47], v30, off
	v_cvt_pk_fp8_f32 v25, v1, v3 op_sel:[0,0,1]
	v_mul_f32_e32 v1, v20, v22
	v_mul_f32_e32 v3, v21, v22
	v_mov_b32_e32 v20, 0
	v_cvt_pk_fp8_f32 v20, v1, v3
	v_mul_f32_e32 v1, v2, v22
	v_mul_f32_e32 v2, v35, v22
	global_store_dword v[46:47], v26, off offset:256
	v_cvt_pk_fp8_f32 v20, v1, v2 op_sel:[0,0,1]
	global_store_dword v[46:47], v25, off offset:512
	global_store_dword v[46:47], v20, off offset:768
	s_and_saveexec_b64 s[16:17], s[6:7]
	s_cbranch_execz .LBB0_209
	v_mul_f32_e32 v0, 0x3b924925, v0
	v_cndmask_b32_e64 v0, 1.0, v0, s[10:11]
	global_store_dword v[44:45], v0, off
	s_branch .LBB0_209
